# FFN up GEMM epilogue: the 8 serialized row-rstd load loops (each waiting behind the previous block's stores) replaced by two up-front load bursts; stores no longer waited on
# baseline (speedup 1.0000x reference)
; __device__ __forceinline__ float row_rstd(const float* rsp, int t, int n4, int fq) {
;     const f32x4* p = (const f32x4*)(rsp + (size_t)t * 64) + fq * n4; float s = 0.f;
;     for (int i = 0; i < n4; ++i) { const f32x4 v = p[i]; s += (v[0] + v[1]) + (v[2] + v[3]); }
;     s += __shfl_xor(s, 16); s += __shfl_xor(s, 32);
;     return rsqrtf(s * (1.0f / D) + EPS);
;     __device__ __forceinline__ void operator()(const f32x4 (&acc)[2][2][4][2], const pg8::Unit& u, int wr, int wc, int fr, int fq) const {
;     ...
;                 const int t = rowb + ai * 128 + m * 16; const float rs = row_rstd(rsp, t, n4, fq);
.LBB0_1078:
	s_lshl_b32 s14, s12, 8
	s_add_i32 s14, s14, s71
	v_or_b32_e32 v142, s14, v147
	v_ashrrev_i32_e32 v143, 31, v142
	v_lshlrev_b64 v[252:253], 8, v[142:143]
	v_lshl_add_u64 v[252:253], v[136:137], 0, v[252:253]
	global_load_dwordx4 v[160:163], v[252:253], off
	global_load_dwordx4 v[164:167], v[252:253], off offset:16
	global_load_dwordx4 v[168:171], v[252:253], off offset:32
	global_load_dwordx4 v[172:175], v[252:253], off offset:48
	v_add_co_u32_e32 v154, vcc, 0x1000, v252
	s_nop 1
	v_addc_co_u32_e32 v155, vcc, 0, v253, vcc
	global_load_dwordx4 v[176:179], v[154:155], off
	global_load_dwordx4 v[180:183], v[154:155], off offset:16
	global_load_dwordx4 v[184:187], v[154:155], off offset:32
	global_load_dwordx4 v[188:191], v[154:155], off offset:48
	v_add_co_u32_e32 v152, vcc, 0x2000, v252
	s_nop 1
	v_addc_co_u32_e32 v153, vcc, 0, v253, vcc
	global_load_dwordx4 v[198:201], v[152:153], off
	global_load_dwordx4 v[202:205], v[152:153], off offset:16
	global_load_dwordx4 v[206:209], v[152:153], off offset:32
	global_load_dwordx4 v[210:213], v[152:153], off offset:48
	v_add_co_u32_e32 v154, vcc, 0x3000, v252
	s_nop 1
	v_addc_co_u32_e32 v155, vcc, 0, v253, vcc
	global_load_dwordx4 v[214:217], v[154:155], off
	global_load_dwordx4 v[224:227], v[154:155], off offset:16
	global_load_dwordx4 v[236:239], v[154:155], off offset:32
	global_load_dwordx4 v[240:243], v[154:155], off offset:48
	s_waitcnt vmcnt(0)
	v_add_f32_e32 v156, v160, v161
	v_add_f32_e32 v157, v162, v163
	v_add_f32_e32 v156, v156, v157
	v_add_f32_e32 v244, 0, v156
	v_add_f32_e32 v156, v164, v165
	v_add_f32_e32 v157, v166, v167
	v_add_f32_e32 v156, v156, v157
	v_add_f32_e32 v244, v244, v156
	s_cmp_eq_u32 s77, 2
	s_cbranch_scc1 .Lup_rs_0
	v_add_f32_e32 v156, v168, v169
	v_add_f32_e32 v157, v170, v171
	v_add_f32_e32 v156, v156, v157
	v_add_f32_e32 v244, v244, v156
	v_add_f32_e32 v156, v172, v173
	v_add_f32_e32 v157, v174, v175
	v_add_f32_e32 v156, v156, v157
	v_add_f32_e32 v244, v244, v156
.Lup_rs_0:
	v_add_f32_e32 v156, v176, v177
	v_add_f32_e32 v157, v178, v179
	v_add_f32_e32 v156, v156, v157
	v_add_f32_e32 v245, 0, v156
	v_add_f32_e32 v156, v180, v181
	v_add_f32_e32 v157, v182, v183
	v_add_f32_e32 v156, v156, v157
	v_add_f32_e32 v245, v245, v156
	s_cmp_eq_u32 s77, 2
	s_cbranch_scc1 .Lup_rs_1
	v_add_f32_e32 v156, v184, v185
	v_add_f32_e32 v157, v186, v187
	v_add_f32_e32 v156, v156, v157
	v_add_f32_e32 v245, v245, v156
	v_add_f32_e32 v156, v188, v189
	v_add_f32_e32 v157, v190, v191
	v_add_f32_e32 v156, v156, v157
	v_add_f32_e32 v245, v245, v156
.Lup_rs_1:
	v_add_f32_e32 v156, v198, v199
	v_add_f32_e32 v157, v200, v201
	v_add_f32_e32 v156, v156, v157
	v_add_f32_e32 v246, 0, v156
	v_add_f32_e32 v156, v202, v203
	v_add_f32_e32 v157, v204, v205
	v_add_f32_e32 v156, v156, v157
	v_add_f32_e32 v246, v246, v156
	s_cmp_eq_u32 s77, 2
	s_cbranch_scc1 .Lup_rs_2
	v_add_f32_e32 v156, v206, v207
	v_add_f32_e32 v157, v208, v209
	v_add_f32_e32 v156, v156, v157
	v_add_f32_e32 v246, v246, v156
	v_add_f32_e32 v156, v210, v211
	v_add_f32_e32 v157, v212, v213
	v_add_f32_e32 v156, v156, v157
	v_add_f32_e32 v246, v246, v156
.Lup_rs_2:
	v_add_f32_e32 v156, v214, v215
	v_add_f32_e32 v157, v216, v217
	v_add_f32_e32 v156, v156, v157
	v_add_f32_e32 v247, 0, v156
	v_add_f32_e32 v156, v224, v225
	v_add_f32_e32 v157, v226, v227
	v_add_f32_e32 v156, v156, v157
	v_add_f32_e32 v247, v247, v156
	s_cmp_eq_u32 s77, 2
	s_cbranch_scc1 .Lup_rs_3
	v_add_f32_e32 v156, v236, v237
	v_add_f32_e32 v157, v238, v239
	v_add_f32_e32 v156, v156, v157
	v_add_f32_e32 v247, v247, v156
	v_add_f32_e32 v156, v240, v241
	v_add_f32_e32 v157, v242, v243
	v_add_f32_e32 v156, v156, v157
	v_add_f32_e32 v247, v247, v156
.Lup_rs_3:
	v_add_co_u32_e32 v152, vcc, 0x8000, v252
	s_nop 1
	v_addc_co_u32_e32 v153, vcc, 0, v253, vcc
	global_load_dwordx4 v[160:163], v[152:153], off
	global_load_dwordx4 v[164:167], v[152:153], off offset:16
	global_load_dwordx4 v[168:171], v[152:153], off offset:32
	global_load_dwordx4 v[172:175], v[152:153], off offset:48
	v_add_co_u32_e32 v154, vcc, 0x9000, v252
	s_nop 1
	v_addc_co_u32_e32 v155, vcc, 0, v253, vcc
	global_load_dwordx4 v[176:179], v[154:155], off
	global_load_dwordx4 v[180:183], v[154:155], off offset:16
	global_load_dwordx4 v[184:187], v[154:155], off offset:32
	global_load_dwordx4 v[188:191], v[154:155], off offset:48
	v_add_co_u32_e32 v152, vcc, 0xa000, v252
	s_nop 1
	v_addc_co_u32_e32 v153, vcc, 0, v253, vcc
	global_load_dwordx4 v[198:201], v[152:153], off
	global_load_dwordx4 v[202:205], v[152:153], off offset:16
	global_load_dwordx4 v[206:209], v[152:153], off offset:32
	global_load_dwordx4 v[210:213], v[152:153], off offset:48
	v_add_co_u32_e32 v154, vcc, 0xb000, v252
	s_nop 1
	v_addc_co_u32_e32 v155, vcc, 0, v253, vcc
	global_load_dwordx4 v[214:217], v[154:155], off
	global_load_dwordx4 v[224:227], v[154:155], off offset:16
	global_load_dwordx4 v[236:239], v[154:155], off offset:32
	global_load_dwordx4 v[240:243], v[154:155], off offset:48
	s_waitcnt vmcnt(0)
	v_add_f32_e32 v156, v160, v161
	v_add_f32_e32 v157, v162, v163
	v_add_f32_e32 v156, v156, v157
	v_add_f32_e32 v248, 0, v156
	v_add_f32_e32 v156, v164, v165
	v_add_f32_e32 v157, v166, v167
	v_add_f32_e32 v156, v156, v157
	v_add_f32_e32 v248, v248, v156
	s_cmp_eq_u32 s77, 2
	s_cbranch_scc1 .Lup_rs_4
	v_add_f32_e32 v156, v168, v169
	v_add_f32_e32 v157, v170, v171
	v_add_f32_e32 v156, v156, v157
	v_add_f32_e32 v248, v248, v156
	v_add_f32_e32 v156, v172, v173
	v_add_f32_e32 v157, v174, v175
	v_add_f32_e32 v156, v156, v157
	v_add_f32_e32 v248, v248, v156
; __device__ __forceinline__ void store8bf(bf16_t* p, f32x4 a, f32x4 b) { u32x4 w; w.x = pk2(a[0], a[1]); w.y = pk2(a[2], a[3]); w.z = pk2(b[0], b[1]); w.w = pk2(b[2], b[3]); *(u32x4*)p = w; }
; __device__ __forceinline__ float row_rstd(const float* rsp, int t, int n4, int fq) {
;     const f32x4* p = (const f32x4*)(rsp + (size_t)t * 64) + fq * n4; float s = 0.f;
;     for (int i = 0; i < n4; ++i) { const f32x4 v = p[i]; s += (v[0] + v[1]) + (v[2] + v[3]); }
;     s += __shfl_xor(s, 16); s += __shfl_xor(s, 32);
;     return rsqrtf(s * (1.0f / D) + EPS);
;     __device__ __forceinline__ void operator()(const f32x4 (&acc)[2][2][4][2], const pg8::Unit& u, int wr, int wc, int fr, int fq) const {
;     ...
;                 const int t = rowb + ai * 128 + m * 16; const float rs = row_rstd(rsp, t, n4, fq);
;                 float* cp = nullptr;
;                 if (!isb) { if (t >= TP - 2 && t < TP) cp = cvp + (size_t)(t - (TP - 2)) * FF + colb; else if (t >= TP && (t & 63) >= 62) cp = cvs + (size_t)(((t - TP) >> 6) * 2 + (t & 63) - 62) * FF + colb; }
; #pragma unroll
;                 for (int bj = 0; bj < 2; ++bj) { const f32x4 v0 = acc[ai][bj][m][0] * rs, v1 = acc[ai][bj][m][1] * rs;
;                     store8bf(dst + (size_t)t * FF + bj * 128, v0, v1);
;                     if (cp) { *(f32x4*)(cp + bj * 128) = v0; *(f32x4*)(cp + bj * 128 + 4) = v1; } }
.Lup_rs_4:
	v_add_f32_e32 v156, v176, v177
	v_add_f32_e32 v157, v178, v179
	v_add_f32_e32 v156, v156, v157
	v_add_f32_e32 v249, 0, v156
	v_add_f32_e32 v156, v180, v181
	v_add_f32_e32 v157, v182, v183
	v_add_f32_e32 v156, v156, v157
	v_add_f32_e32 v249, v249, v156
	s_cmp_eq_u32 s77, 2
	s_cbranch_scc1 .Lup_rs_5
	v_add_f32_e32 v156, v184, v185
	v_add_f32_e32 v157, v186, v187
	v_add_f32_e32 v156, v156, v157
	v_add_f32_e32 v249, v249, v156
	v_add_f32_e32 v156, v188, v189
	v_add_f32_e32 v157, v190, v191
	v_add_f32_e32 v156, v156, v157
	v_add_f32_e32 v249, v249, v156
.Lup_rs_5:
	v_add_f32_e32 v156, v198, v199
	v_add_f32_e32 v157, v200, v201
	v_add_f32_e32 v156, v156, v157
	v_add_f32_e32 v250, 0, v156
	v_add_f32_e32 v156, v202, v203
	v_add_f32_e32 v157, v204, v205
	v_add_f32_e32 v156, v156, v157
	v_add_f32_e32 v250, v250, v156
	s_cmp_eq_u32 s77, 2
	s_cbranch_scc1 .Lup_rs_6
	v_add_f32_e32 v156, v206, v207
	v_add_f32_e32 v157, v208, v209
	v_add_f32_e32 v156, v156, v157
	v_add_f32_e32 v250, v250, v156
	v_add_f32_e32 v156, v210, v211
	v_add_f32_e32 v157, v212, v213
	v_add_f32_e32 v156, v156, v157
	v_add_f32_e32 v250, v250, v156
.Lup_rs_6:
	v_add_f32_e32 v156, v214, v215
	v_add_f32_e32 v157, v216, v217
	v_add_f32_e32 v156, v156, v157
	v_add_f32_e32 v251, 0, v156
	v_add_f32_e32 v156, v224, v225
	v_add_f32_e32 v157, v226, v227
	v_add_f32_e32 v156, v156, v157
	v_add_f32_e32 v251, v251, v156
	s_cmp_eq_u32 s77, 2
	s_cbranch_scc1 .Lup_rs_7
	v_add_f32_e32 v156, v236, v237
	v_add_f32_e32 v157, v238, v239
	v_add_f32_e32 v156, v156, v157
	v_add_f32_e32 v251, v251, v156
	v_add_f32_e32 v156, v240, v241
	v_add_f32_e32 v157, v242, v243
	v_add_f32_e32 v156, v156, v157
	v_add_f32_e32 v251, v251, v156
.Lup_rs_7:
	v_lshlrev_b64 v[144:145], 8, v[142:143]
	v_lshl_add_u64 v[144:145], v[136:137], 0, v[144:145]
	v_mov_b32_e32 v146, 0
	s_mov_b32 s5, s77
.LBB0_1079:
	v_mov_b32_e32 v146, v244
	s_mov_b32 s5, 0
	s_cmp_lg_u32 s5, 0
	v_and_b32_e32 v145, 64, v229
	v_xor_b32_e32 v144, 16, v229
	v_add_u32_e32 v145, 64, v145
	v_cmp_lt_i32_e32 vcc, v144, v145
	v_xor_b32_e32 v153, 32, v229
	s_lshl_b32 s5, s4, 8
	v_cndmask_b32_e32 v144, v229, v144, vcc
	v_lshlrev_b32_e32 v152, 2, v144
	ds_bpermute_b32 v144, v152, v146
	v_cmp_lt_i32_e32 vcc, v153, v145
	s_and_b32 s5, s5, 0xf00
	s_cmp_lt_i32 s4, 16
	v_cndmask_b32_e32 v145, v229, v153, vcc
	v_lshlrev_b32_e32 v153, 2, v145
	s_waitcnt lgkmcnt(0)
	v_add_f32_e32 v144, v146, v144
	ds_bpermute_b32 v145, v153, v144
	s_cselect_b64 s[36:37], -1, 0
	s_cmp_gt_i32 s4, 15
	s_mov_b32 s4, 0x30a00000
	s_cselect_b32 s4, s4, 0x2c600000
	s_waitcnt lgkmcnt(0)
	v_add_f32_e32 v144, v144, v145
	v_fmamk_f32 v144, v144, 0x3a000000, v223
	v_mul_f32_e32 v145, 0x4b800000, v144
	v_cmp_gt_f32_e32 vcc, s97, v144
	v_or_b32_e32 v146, s5, v150
	s_add_u32 s4, s18, s4
	v_cndmask_b32_e32 v144, v144, v145, vcc
	v_rsq_f32_e32 v154, v144
	s_addc_u32 s5, s19, 0
	v_lshlrev_b32_e32 v192, 1, v146
	v_lshl_add_u64 v[144:145], s[4:5], 0, v[192:193]
	v_mul_f32_e32 v155, 0x45800000, v154
	v_cndmask_b32_e32 v154, v154, v155, vcc
	v_lshlrev_b64 v[156:157], 13, v[142:143]
	v_pk_mul_f32 v[126:127], v[126:127], v[154:155] op_sel_hi:[1,0]
	v_pk_mul_f32 v[124:125], v[124:125], v[154:155] op_sel_hi:[1,0]
	v_pk_mul_f32 v[158:159], v[122:123], v[154:155] op_sel_hi:[1,0]
	v_pk_mul_f32 v[122:123], v[120:121], v[154:155] op_sel_hi:[1,0]
	v_lshl_add_u64 v[156:157], v[144:145], 0, v[156:157]
	v_cvt_pk_bf16_f32 v120, v124, v125
	v_cvt_pk_bf16_f32 v121, v126, v127
	v_cvt_pk_bf16_f32 v122, v122, v123
	v_cvt_pk_bf16_f32 v123, v158, v159
	global_store_dwordx4 v[156:157], v[120:123], off
	v_pk_mul_f32 v[118:119], v[118:119], v[154:155] op_sel_hi:[1,0]
	v_pk_mul_f32 v[116:117], v[116:117], v[154:155] op_sel_hi:[1,0]
	v_pk_mul_f32 v[120:121], v[114:115], v[154:155] op_sel_hi:[1,0]
	v_pk_mul_f32 v[114:115], v[112:113], v[154:155] op_sel_hi:[1,0]
	v_cvt_pk_bf16_f32 v112, v116, v117
	v_cvt_pk_bf16_f32 v113, v118, v119
	v_cvt_pk_bf16_f32 v114, v114, v115
	v_cvt_pk_bf16_f32 v115, v120, v121
	global_store_dwordx4 v[156:157], v[112:115], off offset:256
	v_mov_b32_e32 v116, 0
	s_mov_b32 s4, s77
	v_or_b32_e32 v112, 16, v142
	v_ashrrev_i32_e32 v113, 31, v112
	v_lshlrev_b64 v[114:115], 8, v[112:113]
	v_lshl_add_u64 v[114:115], v[136:137], 0, v[114:115]
; __device__ __forceinline__ void store8bf(bf16_t* p, f32x4 a, f32x4 b) { u32x4 w; w.x = pk2(a[0], a[1]); w.y = pk2(a[2], a[3]); w.z = pk2(b[0], b[1]); w.w = pk2(b[2], b[3]); *(u32x4*)p = w; }
; __device__ __forceinline__ float row_rstd(const float* rsp, int t, int n4, int fq) {
;     const f32x4* p = (const f32x4*)(rsp + (size_t)t * 64) + fq * n4; float s = 0.f;
;     for (int i = 0; i < n4; ++i) { const f32x4 v = p[i]; s += (v[0] + v[1]) + (v[2] + v[3]); }
;     s += __shfl_xor(s, 16); s += __shfl_xor(s, 32);
;     return rsqrtf(s * (1.0f / D) + EPS);
;     __device__ __forceinline__ void operator()(const f32x4 (&acc)[2][2][4][2], const pg8::Unit& u, int wr, int wc, int fr, int fq) const {
;     ...
;                 const int t = rowb + ai * 128 + m * 16; const float rs = row_rstd(rsp, t, n4, fq);
;                 float* cp = nullptr;
;                 if (!isb) { if (t >= TP - 2 && t < TP) cp = cvp + (size_t)(t - (TP - 2)) * FF + colb; else if (t >= TP && (t & 63) >= 62) cp = cvs + (size_t)(((t - TP) >> 6) * 2 + (t & 63) - 62) * FF + colb; }
; #pragma unroll
;                 for (int bj = 0; bj < 2; ++bj) { const f32x4 v0 = acc[ai][bj][m][0] * rs, v1 = acc[ai][bj][m][1] * rs;
;                     store8bf(dst + (size_t)t * FF + bj * 128, v0, v1);
;                     if (cp) { *(f32x4*)(cp + bj * 128) = v0; *(f32x4*)(cp + bj * 128 + 4) = v1; } }
.LBB0_1081:
	v_mov_b32_e32 v116, v245
	s_mov_b32 s4, 0
	s_cmp_lg_u32 s4, 0
	ds_bpermute_b32 v114, v152, v116
	v_lshlrev_b64 v[112:113], 13, v[112:113]
	v_lshl_add_u64 v[112:113], v[144:145], 0, v[112:113]
	s_mov_b32 s4, s77
	s_waitcnt lgkmcnt(0)
	v_add_f32_e32 v114, v116, v114
	ds_bpermute_b32 v115, v153, v114
	s_waitcnt lgkmcnt(0)
	v_add_f32_e32 v114, v114, v115
	v_fmamk_f32 v114, v114, 0x3a000000, v223
	v_mul_f32_e32 v115, 0x4b800000, v114
	v_cmp_gt_f32_e32 vcc, s97, v114
	s_nop 1
	v_cndmask_b32_e32 v114, v114, v115, vcc
	v_rsq_f32_e32 v114, v114
	s_nop 0
	v_mul_f32_e32 v115, 0x45800000, v114
	v_cndmask_b32_e32 v114, v114, v115, vcc
	v_pk_mul_f32 v[110:111], v[110:111], v[114:115] op_sel_hi:[1,0]
	v_pk_mul_f32 v[108:109], v[108:109], v[114:115] op_sel_hi:[1,0]
	v_pk_mul_f32 v[106:107], v[106:107], v[114:115] op_sel_hi:[1,0]
	v_pk_mul_f32 v[104:105], v[104:105], v[114:115] op_sel_hi:[1,0]
	v_pk_mul_f32 v[116:117], v[102:103], v[114:115] op_sel_hi:[1,0]
	v_pk_mul_f32 v[118:119], v[100:101], v[114:115] op_sel_hi:[1,0]
	v_cvt_pk_bf16_f32 v100, v108, v109
	v_cvt_pk_bf16_f32 v101, v110, v111
	v_cvt_pk_bf16_f32 v102, v104, v105
	v_cvt_pk_bf16_f32 v103, v106, v107
	global_store_dwordx4 v[112:113], v[100:103], off
	s_nop 1
	v_pk_mul_f32 v[100:101], v[98:99], v[114:115] op_sel_hi:[1,0]
	v_pk_mul_f32 v[98:99], v[96:97], v[114:115] op_sel_hi:[1,0]
	v_cvt_pk_bf16_f32 v96, v118, v119
	v_cvt_pk_bf16_f32 v97, v116, v117
	v_cvt_pk_bf16_f32 v98, v98, v99
	v_cvt_pk_bf16_f32 v99, v100, v101
	global_store_dwordx4 v[112:113], v[96:99], off offset:256
	v_mov_b32_e32 v100, 0
	s_nop 0
	v_or_b32_e32 v96, 32, v142
	v_ashrrev_i32_e32 v97, 31, v96
	v_lshlrev_b64 v[98:99], 8, v[96:97]
	v_lshl_add_u64 v[98:99], v[136:137], 0, v[98:99]
.LBB0_1083:
	v_mov_b32_e32 v100, v246
	s_mov_b32 s4, 0
	s_cmp_lg_u32 s4, 0
	ds_bpermute_b32 v98, v152, v100
	v_lshlrev_b64 v[96:97], 13, v[96:97]
	v_lshl_add_u64 v[96:97], v[144:145], 0, v[96:97]
	s_mov_b32 s4, s77
	s_waitcnt lgkmcnt(0)
	v_add_f32_e32 v98, v100, v98
	ds_bpermute_b32 v99, v153, v98
	s_waitcnt lgkmcnt(0)
	v_add_f32_e32 v98, v98, v99
	v_fmamk_f32 v98, v98, 0x3a000000, v223
	v_mul_f32_e32 v99, 0x4b800000, v98
	v_cmp_gt_f32_e32 vcc, s97, v98
	s_nop 1
	v_cndmask_b32_e32 v98, v98, v99, vcc
	v_rsq_f32_e32 v98, v98
	s_nop 0
	v_mul_f32_e32 v99, 0x45800000, v98
	v_cndmask_b32_e32 v98, v98, v99, vcc
	v_pk_mul_f32 v[94:95], v[94:95], v[98:99] op_sel_hi:[1,0]
	v_pk_mul_f32 v[92:93], v[92:93], v[98:99] op_sel_hi:[1,0]
	v_pk_mul_f32 v[90:91], v[90:91], v[98:99] op_sel_hi:[1,0]
	v_pk_mul_f32 v[88:89], v[88:89], v[98:99] op_sel_hi:[1,0]
	v_pk_mul_f32 v[100:101], v[86:87], v[98:99] op_sel_hi:[1,0]
	v_pk_mul_f32 v[102:103], v[84:85], v[98:99] op_sel_hi:[1,0]
	v_cvt_pk_bf16_f32 v84, v92, v93
	v_cvt_pk_bf16_f32 v85, v94, v95
	v_cvt_pk_bf16_f32 v86, v88, v89
	v_cvt_pk_bf16_f32 v87, v90, v91
	global_store_dwordx4 v[96:97], v[84:87], off
	s_nop 1
	v_pk_mul_f32 v[84:85], v[82:83], v[98:99] op_sel_hi:[1,0]
	v_pk_mul_f32 v[82:83], v[80:81], v[98:99] op_sel_hi:[1,0]
	v_cvt_pk_bf16_f32 v80, v102, v103
	v_cvt_pk_bf16_f32 v82, v82, v83
	v_cvt_pk_bf16_f32 v83, v84, v85
	v_or_b32_e32 v84, 48, v142
	v_cvt_pk_bf16_f32 v81, v100, v101
	v_ashrrev_i32_e32 v85, 31, v84
	global_store_dwordx4 v[96:97], v[80:83], off offset:256
	s_nop 1
	v_lshlrev_b64 v[80:81], 8, v[84:85]
	v_lshl_add_u64 v[80:81], v[136:137], 0, v[80:81]
	v_mov_b32_e32 v82, 0
.LBB0_1085:
	v_mov_b32_e32 v82, v247
	s_mov_b32 s4, 0
	s_cmp_lg_u32 s4, 0
	ds_bpermute_b32 v83, v152, v82
	v_lshlrev_b32_e32 v192, 2, v146
	v_lshl_add_u64 v[80:81], s[16:17], 0, v[192:193]
	s_andn2_b64 vcc, exec, s[36:37]
	s_waitcnt lgkmcnt(0)
	v_add_f32_e32 v86, v82, v83
	ds_bpermute_b32 v87, v153, v86
	v_cndmask_b32_e64 v82, 0, 1, s[36:37]
	v_cmp_ne_u32_e64 s[12:13], 1, v82
	v_mov_b64_e32 v[82:83], 0
	s_cbranch_vccnz .LBB0_1092
	v_and_b32_e32 v82, -2, v84
	v_cmp_ne_u32_e32 vcc, s50, v82
	s_and_saveexec_b64 s[4:5], vcc
	s_xor_b64 s[4:5], exec, s[4:5]
	s_cbranch_execz .LBB0_1089
	s_add_i32 s15, s14, 0xffffe000
	s_lshr_b32 s15, s15, 5
	s_movk_i32 s36, 0x1fff
	v_add_u32_e32 v82, s15, v149
	v_mov_b32_e32 v83, v193
	v_cmp_lt_i32_e32 vcc, s36, v84
	v_lshlrev_b64 v[82:83], 14, v[82:83]
	v_lshl_add_u64 v[82:83], v[80:81], 0, v[82:83]
	s_and_b64 vcc, vcc, s[8:9]
	v_cndmask_b32_e32 v83, 0, v83, vcc
	v_cndmask_b32_e32 v82, 0, v82, vcc

; __device__ __forceinline__ void store8bf(bf16_t* p, f32x4 a, f32x4 b) { u32x4 w; w.x = pk2(a[0], a[1]); w.y = pk2(a[2], a[3]); w.z = pk2(b[0], b[1]); w.w = pk2(b[2], b[3]); *(u32x4*)p = w; }
; __device__ __forceinline__ float row_rstd(const float* rsp, int t, int n4, int fq) {
;     const f32x4* p = (const f32x4*)(rsp + (size_t)t * 64) + fq * n4; float s = 0.f;
;     for (int i = 0; i < n4; ++i) { const f32x4 v = p[i]; s += (v[0] + v[1]) + (v[2] + v[3]); }
;     s += __shfl_xor(s, 16); s += __shfl_xor(s, 32);
;     return rsqrtf(s * (1.0f / D) + EPS);
;     __device__ __forceinline__ void operator()(const f32x4 (&acc)[2][2][4][2], const pg8::Unit& u, int wr, int wc, int fr, int fq) const {
;     ...
;                 const int t = rowb + ai * 128 + m * 16; const float rs = row_rstd(rsp, t, n4, fq);
;                 float* cp = nullptr;
;                 if (!isb) { if (t >= TP - 2 && t < TP) cp = cvp + (size_t)(t - (TP - 2)) * FF + colb; else if (t >= TP && (t & 63) >= 62) cp = cvs + (size_t)(((t - TP) >> 6) * 2 + (t & 63) - 62) * FF + colb; }
; #pragma unroll
;                 for (int bj = 0; bj < 2; ++bj) { const f32x4 v0 = acc[ai][bj][m][0] * rs, v1 = acc[ai][bj][m][1] * rs;
;                     store8bf(dst + (size_t)t * FF + bj * 128, v0, v1);
;                     if (cp) { *(f32x4*)(cp + bj * 128) = v0; *(f32x4*)(cp + bj * 128 + 4) = v1; } }
.LBB0_1097:
	v_mov_b32_e32 v68, v248
	s_mov_b32 s4, 0
	s_cmp_lg_u32 s4, 0
	ds_bpermute_b32 v66, v152, v68
	v_lshlrev_b64 v[64:65], 13, v[64:65]
	v_lshl_add_u64 v[64:65], v[144:145], 0, v[64:65]
	s_mov_b32 s4, s77
	s_waitcnt lgkmcnt(0)
	v_add_f32_e32 v66, v68, v66
	ds_bpermute_b32 v67, v153, v66
	s_waitcnt lgkmcnt(0)
	v_add_f32_e32 v66, v66, v67
	v_fmamk_f32 v66, v66, 0x3a000000, v223
	v_mul_f32_e32 v67, 0x4b800000, v66
	v_cmp_gt_f32_e32 vcc, s97, v66
	s_nop 1
	v_cndmask_b32_e32 v66, v66, v67, vcc
	v_rsq_f32_e32 v66, v66
	s_nop 0
	v_mul_f32_e32 v67, 0x45800000, v66
	v_cndmask_b32_e32 v66, v66, v67, vcc
	v_pk_mul_f32 v[62:63], v[62:63], v[66:67] op_sel_hi:[1,0]
	v_pk_mul_f32 v[60:61], v[60:61], v[66:67] op_sel_hi:[1,0]
	v_pk_mul_f32 v[58:59], v[58:59], v[66:67] op_sel_hi:[1,0]
	v_pk_mul_f32 v[56:57], v[56:57], v[66:67] op_sel_hi:[1,0]
	v_pk_mul_f32 v[68:69], v[54:55], v[66:67] op_sel_hi:[1,0]
	v_pk_mul_f32 v[70:71], v[52:53], v[66:67] op_sel_hi:[1,0]
	v_cvt_pk_bf16_f32 v52, v60, v61
	v_cvt_pk_bf16_f32 v53, v62, v63
	v_cvt_pk_bf16_f32 v54, v56, v57
	v_cvt_pk_bf16_f32 v55, v58, v59
	global_store_dwordx4 v[64:65], v[52:55], off
	s_nop 1
	v_pk_mul_f32 v[52:53], v[50:51], v[66:67] op_sel_hi:[1,0]
	v_pk_mul_f32 v[50:51], v[48:49], v[66:67] op_sel_hi:[1,0]
	v_cvt_pk_bf16_f32 v48, v70, v71
	v_cvt_pk_bf16_f32 v49, v68, v69
	v_cvt_pk_bf16_f32 v50, v50, v51
	v_cvt_pk_bf16_f32 v51, v52, v53
	global_store_dwordx4 v[64:65], v[48:51], off offset:256
	v_mov_b32_e32 v52, 0
	s_nop 0
	v_add_u32_e32 v48, 0x90, v142
	v_ashrrev_i32_e32 v49, 31, v48
	v_lshlrev_b64 v[50:51], 8, v[48:49]
	v_lshl_add_u64 v[50:51], v[136:137], 0, v[50:51]
.LBB0_1099:
	v_mov_b32_e32 v52, v249
	s_mov_b32 s4, 0
	s_cmp_lg_u32 s4, 0
	ds_bpermute_b32 v50, v152, v52
	v_lshlrev_b64 v[48:49], 13, v[48:49]
	v_lshl_add_u64 v[48:49], v[144:145], 0, v[48:49]
	s_mov_b32 s4, s77
	s_waitcnt lgkmcnt(0)
	v_add_f32_e32 v50, v52, v50
	ds_bpermute_b32 v51, v153, v50
	s_waitcnt lgkmcnt(0)
	v_add_f32_e32 v50, v50, v51
	v_fmamk_f32 v50, v50, 0x3a000000, v223
	v_mul_f32_e32 v51, 0x4b800000, v50
	v_cmp_gt_f32_e32 vcc, s97, v50
	s_nop 1
	v_cndmask_b32_e32 v50, v50, v51, vcc
	v_rsq_f32_e32 v50, v50
	s_nop 0
	v_mul_f32_e32 v51, 0x45800000, v50
	v_cndmask_b32_e32 v50, v50, v51, vcc
	v_pk_mul_f32 v[46:47], v[46:47], v[50:51] op_sel_hi:[1,0]
	v_pk_mul_f32 v[44:45], v[44:45], v[50:51] op_sel_hi:[1,0]
	v_pk_mul_f32 v[42:43], v[42:43], v[50:51] op_sel_hi:[1,0]
	v_pk_mul_f32 v[40:41], v[40:41], v[50:51] op_sel_hi:[1,0]
	v_pk_mul_f32 v[52:53], v[38:39], v[50:51] op_sel_hi:[1,0]
	v_pk_mul_f32 v[54:55], v[36:37], v[50:51] op_sel_hi:[1,0]
	v_cvt_pk_bf16_f32 v36, v44, v45
	v_cvt_pk_bf16_f32 v37, v46, v47
	v_cvt_pk_bf16_f32 v38, v40, v41
	v_cvt_pk_bf16_f32 v39, v42, v43
	global_store_dwordx4 v[48:49], v[36:39], off
	s_nop 1
	v_pk_mul_f32 v[36:37], v[34:35], v[50:51] op_sel_hi:[1,0]
	v_pk_mul_f32 v[34:35], v[32:33], v[50:51] op_sel_hi:[1,0]
	v_cvt_pk_bf16_f32 v32, v54, v55
	v_cvt_pk_bf16_f32 v33, v52, v53
	v_cvt_pk_bf16_f32 v34, v34, v35
	v_cvt_pk_bf16_f32 v35, v36, v37
	global_store_dwordx4 v[48:49], v[32:35], off offset:256
	v_mov_b32_e32 v36, 0
	s_nop 0
	v_add_u32_e32 v32, 0xa0, v142
	v_ashrrev_i32_e32 v33, 31, v32
	v_lshlrev_b64 v[34:35], 8, v[32:33]
	v_lshl_add_u64 v[34:35], v[136:137], 0, v[34:35]
.LBB0_1101:
	v_mov_b32_e32 v36, v250
	s_mov_b32 s4, 0
	s_cmp_lg_u32 s4, 0
	ds_bpermute_b32 v34, v152, v36
	v_lshlrev_b64 v[32:33], 13, v[32:33]
	v_lshl_add_u64 v[32:33], v[144:145], 0, v[32:33]
	s_mov_b32 s4, s77
	s_waitcnt lgkmcnt(0)
	v_add_f32_e32 v34, v36, v34
	ds_bpermute_b32 v35, v153, v34
	s_waitcnt lgkmcnt(0)
	v_add_f32_e32 v34, v34, v35
	v_fmamk_f32 v34, v34, 0x3a000000, v223
	v_mul_f32_e32 v35, 0x4b800000, v34
	v_cmp_gt_f32_e32 vcc, s97, v34
	s_nop 1
	v_cndmask_b32_e32 v34, v34, v35, vcc
	v_rsq_f32_e32 v34, v34
	s_nop 0
	v_mul_f32_e32 v35, 0x45800000, v34
	v_cndmask_b32_e32 v34, v34, v35, vcc
	v_pk_mul_f32 v[30:31], v[30:31], v[34:35] op_sel_hi:[1,0]
	v_pk_mul_f32 v[28:29], v[28:29], v[34:35] op_sel_hi:[1,0]
	v_pk_mul_f32 v[26:27], v[26:27], v[34:35] op_sel_hi:[1,0]
	v_pk_mul_f32 v[24:25], v[24:25], v[34:35] op_sel_hi:[1,0]
	v_pk_mul_f32 v[36:37], v[22:23], v[34:35] op_sel_hi:[1,0]
	v_pk_mul_f32 v[38:39], v[20:21], v[34:35] op_sel_hi:[1,0]
	v_cvt_pk_bf16_f32 v20, v28, v29
	v_cvt_pk_bf16_f32 v21, v30, v31
	v_cvt_pk_bf16_f32 v22, v24, v25
	v_cvt_pk_bf16_f32 v23, v26, v27
	global_store_dwordx4 v[32:33], v[20:23], off
	s_nop 1
	v_pk_mul_f32 v[20:21], v[18:19], v[34:35] op_sel_hi:[1,0]
	v_pk_mul_f32 v[18:19], v[16:17], v[34:35] op_sel_hi:[1,0]
	v_cvt_pk_bf16_f32 v16, v38, v39
	v_cvt_pk_bf16_f32 v17, v36, v37
	v_cvt_pk_bf16_f32 v18, v18, v19
	v_cvt_pk_bf16_f32 v19, v20, v21
	global_store_dwordx4 v[32:33], v[16:19], off offset:256
	v_mov_b32_e32 v20, 0
	s_nop 0
	v_add_u32_e32 v18, 0xb0, v142
	v_ashrrev_i32_e32 v19, 31, v18
	v_lshlrev_b64 v[16:17], 8, v[18:19]
	v_lshl_add_u64 v[16:17], v[136:137], 0, v[16:17]
.LBB0_1103:
	v_mov_b32_e32 v20, v251
	s_mov_b32 s4, 0
	s_cmp_lg_u32 s4, 0
	ds_bpermute_b32 v16, v152, v20
	s_and_b64 vcc, exec, s[12:13]
	s_waitcnt lgkmcnt(0)
	v_add_f32_e32 v20, v20, v16
	ds_bpermute_b32 v21, v153, v20
	v_mov_b64_e32 v[16:17], 0
	s_cbranch_vccnz .LBB0_1110
	v_and_b32_e32 v16, -2, v18
	v_cmp_ne_u32_e32 vcc, s50, v16
	s_and_saveexec_b64 s[4:5], vcc
	s_xor_b64 s[4:5], exec, s[4:5]
	s_cbranch_execz .LBB0_1107
	s_addk_i32 s14, 0xe080
	s_lshr_b32 s12, s14, 5
	s_movk_i32 s13, 0x1f4f
	v_add_u32_e32 v192, s12, v149
	v_cmp_lt_i32_e32 vcc, s13, v142
	v_lshlrev_b64 v[16:17], 14, v[192:193]
	v_lshl_add_u64 v[16:17], v[80:81], 0, v[16:17]
	s_and_b64 vcc, vcc, s[8:9]
	v_cndmask_b32_e32 v17, 0, v17, vcc
	v_cndmask_b32_e32 v16, 0, v16, vcc
